# v20: accumulate-chain MFMA order, row-fragment major (first source repeats with period 2), in the K-loop bodies + SwiGLU epilogue and mixer staging VALU reductions
# baseline (speedup 1.0000x reference)
.LBB0_402:
	s_lshl_b32 s54, s41, 7
	s_add_u32 s55, s66, s54
	s_addc_u32 s56, s67, 0
	s_add_u32 s58, s55, 0x100
	ds_read_b128 v[146:149], v142
	ds_read_b128 v[150:153], v142 offset:1024
	ds_read_b128 v[154:157], v142 offset:2048
	ds_read_b128 v[158:161], v142 offset:3072
	ds_read_b128 v[162:165], v143
	ds_read_b128 v[166:169], v143 offset:1024
	ds_read_b128 v[172:175], v143 offset:2048
	ds_read_b128 v[176:179], v143 offset:3072
	s_addc_u32 s59, s56, 0
	s_and_b64 s[52:53], s[84:85], exec
	s_cselect_b32 s91, s43, s59
	s_cselect_b32 s90, s44, s58
	s_add_u32 s52, s12, s54
	s_addc_u32 s53, s13, 0
	s_add_u32 s54, s52, 0x100
	s_addc_u32 s58, s53, 0
	s_and_b64 s[52:53], s[84:85], exec
	s_cselect_b32 s85, s45, s58
	s_cselect_b32 s84, s47, s54
	s_add_u32 s86, s90, 0x80
	s_addc_u32 s87, s91, 0
	s_waitcnt lgkmcnt(0)
	s_add_u32 s88, s84, 0x80
	s_addc_u32 s89, s85, 0
	ds_read_b128 v[180:183], v141
	ds_read_b128 v[184:187], v141 offset:1024
	ds_read_b128 v[188:191], v141 offset:2048
	ds_read_b128 v[196:199], v141 offset:3072
	ds_read_b128 v[200:203], v141 offset:4096
	ds_read_b128 v[204:207], v141 offset:5120
	ds_read_b128 v[208:211], v141 offset:6144
	ds_read_b128 v[212:215], v141 offset:7168
	s_add_u32 s52, s55, 0x40080
	s_addc_u32 s53, s56, 0
	s_add_i32 m0, s16, 0xc000
	s_nop 0
	global_load_lds_dwordx4 v136, s[52:53]
	s_nop 0
	s_add_i32 m0, s16, 0xe000
	s_nop 0
	global_load_lds_dwordx4 v137, s[52:53]
	s_waitcnt vmcnt(8)
	s_waitcnt lgkmcnt(0)
	s_setprio 1
	s_barrier
	v_mfma_f32_16x16x32_bf16 v[128:131], v[146:149], v[180:183], v[128:131]
	v_mfma_f32_16x16x32_bf16 v[128:131], v[150:153], v[184:187], v[128:131]
	v_mfma_f32_16x16x32_bf16 v[112:115], v[146:149], v[188:191], v[112:115]
	v_mfma_f32_16x16x32_bf16 v[112:115], v[150:153], v[196:199], v[112:115]
	v_mfma_f32_16x16x32_bf16 v[96:99], v[146:149], v[200:203], v[96:99]
	v_mfma_f32_16x16x32_bf16 v[96:99], v[150:153], v[204:207], v[96:99]
	v_mfma_f32_16x16x32_bf16 v[64:67], v[146:149], v[208:211], v[64:67]
	v_mfma_f32_16x16x32_bf16 v[64:67], v[150:153], v[212:215], v[64:67]
	v_mfma_f32_16x16x32_bf16 v[120:123], v[154:157], v[180:183], v[120:123]
	v_mfma_f32_16x16x32_bf16 v[120:123], v[158:161], v[184:187], v[120:123]
	v_mfma_f32_16x16x32_bf16 v[104:107], v[154:157], v[188:191], v[104:107]
	v_mfma_f32_16x16x32_bf16 v[104:107], v[158:161], v[196:199], v[104:107]
	v_mfma_f32_16x16x32_bf16 v[88:91], v[154:157], v[200:203], v[88:91]
	v_mfma_f32_16x16x32_bf16 v[88:91], v[158:161], v[204:207], v[88:91]
	v_mfma_f32_16x16x32_bf16 v[56:59], v[154:157], v[208:211], v[56:59]
	v_mfma_f32_16x16x32_bf16 v[56:59], v[158:161], v[212:215], v[56:59]
	v_mfma_f32_16x16x32_bf16 v[124:127], v[162:165], v[180:183], v[124:127]
	v_mfma_f32_16x16x32_bf16 v[124:127], v[166:169], v[184:187], v[124:127]
	v_mfma_f32_16x16x32_bf16 v[108:111], v[162:165], v[188:191], v[108:111]
	v_mfma_f32_16x16x32_bf16 v[108:111], v[166:169], v[196:199], v[108:111]
	v_mfma_f32_16x16x32_bf16 v[92:95], v[162:165], v[200:203], v[92:95]
	v_mfma_f32_16x16x32_bf16 v[92:95], v[166:169], v[204:207], v[92:95]
	v_mfma_f32_16x16x32_bf16 v[60:63], v[162:165], v[208:211], v[60:63]
	v_mfma_f32_16x16x32_bf16 v[60:63], v[166:169], v[212:215], v[60:63]
	v_mfma_f32_16x16x32_bf16 v[116:119], v[172:175], v[180:183], v[116:119]
	v_mfma_f32_16x16x32_bf16 v[116:119], v[176:179], v[184:187], v[116:119]
	v_mfma_f32_16x16x32_bf16 v[100:103], v[172:175], v[188:191], v[100:103]
	v_mfma_f32_16x16x32_bf16 v[100:103], v[176:179], v[196:199], v[100:103]
	v_mfma_f32_16x16x32_bf16 v[84:87], v[172:175], v[200:203], v[84:87]
	v_mfma_f32_16x16x32_bf16 v[84:87], v[176:179], v[204:207], v[84:87]
	v_mfma_f32_16x16x32_bf16 v[52:55], v[172:175], v[208:211], v[52:55]
	v_mfma_f32_16x16x32_bf16 v[52:55], v[176:179], v[212:215], v[52:55]
	s_barrier
	s_setprio 0
	ds_read_b128 v[180:183], v141 offset:16384
	ds_read_b128 v[184:187], v141 offset:17408
	ds_read_b128 v[188:191], v141 offset:18432
	ds_read_b128 v[196:199], v141 offset:19456
	ds_read_b128 v[200:203], v141 offset:20480
	ds_read_b128 v[204:207], v141 offset:21504
	ds_read_b128 v[208:211], v141 offset:22528
	ds_read_b128 v[212:215], v141 offset:23552
	s_add_i32 m0, s16, 0x10000
	s_nop 0
	global_load_lds_dwordx4 v1, s[84:85]
	s_nop 0
	s_add_i32 m0, s16, 0x12000
	s_nop 0
	global_load_lds_dwordx4 v134, s[84:85]
	s_add_u32 s52, s84, 0x40000
	s_addc_u32 s53, s85, 0
	s_add_i32 m0, s16, 0x14000
	s_nop 0
	global_load_lds_dwordx4 v1, s[52:53]
	s_nop 0
	s_add_i32 m0, s16, 0x16000
	s_nop 0
	global_load_lds_dwordx4 v134, s[52:53]
	s_nop 0
	s_add_i32 m0, s16, 0
	s_nop 0
	global_load_lds_dwordx4 v136, s[90:91]
	s_nop 0
	s_add_i32 m0, s16, 0x2000
	s_nop 0
	global_load_lds_dwordx4 v137, s[90:91]
	s_waitcnt vmcnt(8)
	s_waitcnt lgkmcnt(0)
	s_setprio 1
	s_barrier
	v_mfma_f32_16x16x32_bf16 v[80:83], v[146:149], v[180:183], v[80:83]
	v_mfma_f32_16x16x32_bf16 v[80:83], v[150:153], v[184:187], v[80:83]
	v_mfma_f32_16x16x32_bf16 v[48:51], v[146:149], v[188:191], v[48:51]
	v_mfma_f32_16x16x32_bf16 v[48:51], v[150:153], v[196:199], v[48:51]
	v_mfma_f32_16x16x32_bf16 v[32:35], v[146:149], v[200:203], v[32:35]
	v_mfma_f32_16x16x32_bf16 v[32:35], v[150:153], v[204:207], v[32:35]
	v_mfma_f32_16x16x32_bf16 v[16:19], v[146:149], v[208:211], v[16:19]
	v_mfma_f32_16x16x32_bf16 v[16:19], v[150:153], v[212:215], v[16:19]
	v_mfma_f32_16x16x32_bf16 v[72:75], v[154:157], v[180:183], v[72:75]
	v_mfma_f32_16x16x32_bf16 v[72:75], v[158:161], v[184:187], v[72:75]
	v_mfma_f32_16x16x32_bf16 v[40:43], v[154:157], v[188:191], v[40:43]
	v_mfma_f32_16x16x32_bf16 v[40:43], v[158:161], v[196:199], v[40:43]
	v_mfma_f32_16x16x32_bf16 v[24:27], v[154:157], v[200:203], v[24:27]
	v_mfma_f32_16x16x32_bf16 v[24:27], v[158:161], v[204:207], v[24:27]
	v_mfma_f32_16x16x32_bf16 v[8:11], v[154:157], v[208:211], v[8:11]
	v_mfma_f32_16x16x32_bf16 v[8:11], v[158:161], v[212:215], v[8:11]
	v_mfma_f32_16x16x32_bf16 v[76:79], v[162:165], v[180:183], v[76:79]
	v_mfma_f32_16x16x32_bf16 v[76:79], v[166:169], v[184:187], v[76:79]
	v_mfma_f32_16x16x32_bf16 v[44:47], v[162:165], v[188:191], v[44:47]
	v_mfma_f32_16x16x32_bf16 v[44:47], v[166:169], v[196:199], v[44:47]
	v_mfma_f32_16x16x32_bf16 v[28:31], v[162:165], v[200:203], v[28:31]
	v_mfma_f32_16x16x32_bf16 v[28:31], v[166:169], v[204:207], v[28:31]
	v_mfma_f32_16x16x32_bf16 v[12:15], v[162:165], v[208:211], v[12:15]
	v_mfma_f32_16x16x32_bf16 v[12:15], v[166:169], v[212:215], v[12:15]
	v_mfma_f32_16x16x32_bf16 v[68:71], v[172:175], v[180:183], v[68:71]
	v_mfma_f32_16x16x32_bf16 v[68:71], v[176:179], v[184:187], v[68:71]
	v_mfma_f32_16x16x32_bf16 v[36:39], v[172:175], v[188:191], v[36:39]
	v_mfma_f32_16x16x32_bf16 v[36:39], v[176:179], v[196:199], v[36:39]
	v_mfma_f32_16x16x32_bf16 v[20:23], v[172:175], v[200:203], v[20:23]
	v_mfma_f32_16x16x32_bf16 v[20:23], v[176:179], v[204:207], v[20:23]
	v_mfma_f32_16x16x32_bf16 v[4:7], v[172:175], v[208:211], v[4:7]
	v_mfma_f32_16x16x32_bf16 v[4:7], v[176:179], v[212:215], v[4:7]
	s_barrier
	s_setprio 0
	ds_read_b128 v[146:149], v144
	ds_read_b128 v[150:153], v144 offset:1024
	ds_read_b128 v[154:157], v144 offset:2048
	ds_read_b128 v[158:161], v144 offset:3072
	ds_read_b128 v[162:165], v145
	ds_read_b128 v[166:169], v145 offset:1024
	ds_read_b128 v[172:175], v145 offset:2048
	ds_read_b128 v[176:179], v145 offset:3072
	ds_read_b128 v[180:183], v141 offset:32768
	ds_read_b128 v[184:187], v141 offset:33792
	ds_read_b128 v[188:191], v141 offset:34816
	ds_read_b128 v[196:199], v141 offset:35840
	ds_read_b128 v[200:203], v141 offset:36864
	ds_read_b128 v[204:207], v141 offset:37888
	ds_read_b128 v[208:211], v141 offset:38912
	ds_read_b128 v[212:215], v141 offset:39936
	s_add_u32 s52, s90, 0x40000
	s_addc_u32 s53, s91, 0
	s_add_i32 m0, s16, 0x4000
	s_nop 0
	global_load_lds_dwordx4 v136, s[52:53]
	s_nop 0
	s_add_i32 m0, s16, 0x6000
	s_nop 0
	global_load_lds_dwordx4 v137, s[52:53]
	s_waitcnt vmcnt(8)
	s_waitcnt lgkmcnt(0)
	s_setprio 1
	s_barrier
	v_mfma_f32_16x16x32_bf16 v[128:131], v[146:149], v[180:183], v[128:131]
	v_mfma_f32_16x16x32_bf16 v[128:131], v[150:153], v[184:187], v[128:131]
	v_mfma_f32_16x16x32_bf16 v[112:115], v[146:149], v[188:191], v[112:115]
	v_mfma_f32_16x16x32_bf16 v[112:115], v[150:153], v[196:199], v[112:115]
	v_mfma_f32_16x16x32_bf16 v[96:99], v[146:149], v[200:203], v[96:99]
	v_mfma_f32_16x16x32_bf16 v[96:99], v[150:153], v[204:207], v[96:99]
	v_mfma_f32_16x16x32_bf16 v[64:67], v[146:149], v[208:211], v[64:67]
	v_mfma_f32_16x16x32_bf16 v[64:67], v[150:153], v[212:215], v[64:67]
	v_mfma_f32_16x16x32_bf16 v[120:123], v[154:157], v[180:183], v[120:123]
	v_mfma_f32_16x16x32_bf16 v[120:123], v[158:161], v[184:187], v[120:123]
	v_mfma_f32_16x16x32_bf16 v[104:107], v[154:157], v[188:191], v[104:107]
	v_mfma_f32_16x16x32_bf16 v[104:107], v[158:161], v[196:199], v[104:107]
	v_mfma_f32_16x16x32_bf16 v[88:91], v[154:157], v[200:203], v[88:91]
	v_mfma_f32_16x16x32_bf16 v[88:91], v[158:161], v[204:207], v[88:91]
	v_mfma_f32_16x16x32_bf16 v[56:59], v[154:157], v[208:211], v[56:59]
	v_mfma_f32_16x16x32_bf16 v[56:59], v[158:161], v[212:215], v[56:59]
	v_mfma_f32_16x16x32_bf16 v[124:127], v[162:165], v[180:183], v[124:127]
	v_mfma_f32_16x16x32_bf16 v[124:127], v[166:169], v[184:187], v[124:127]
	v_mfma_f32_16x16x32_bf16 v[108:111], v[162:165], v[188:191], v[108:111]
	v_mfma_f32_16x16x32_bf16 v[108:111], v[166:169], v[196:199], v[108:111]
	v_mfma_f32_16x16x32_bf16 v[92:95], v[162:165], v[200:203], v[92:95]
	v_mfma_f32_16x16x32_bf16 v[92:95], v[166:169], v[204:207], v[92:95]
	v_mfma_f32_16x16x32_bf16 v[60:63], v[162:165], v[208:211], v[60:63]
	v_mfma_f32_16x16x32_bf16 v[60:63], v[166:169], v[212:215], v[60:63]
	v_mfma_f32_16x16x32_bf16 v[116:119], v[172:175], v[180:183], v[116:119]
	v_mfma_f32_16x16x32_bf16 v[116:119], v[176:179], v[184:187], v[116:119]
	v_mfma_f32_16x16x32_bf16 v[100:103], v[172:175], v[188:191], v[100:103]
	v_mfma_f32_16x16x32_bf16 v[100:103], v[176:179], v[196:199], v[100:103]
	v_mfma_f32_16x16x32_bf16 v[84:87], v[172:175], v[200:203], v[84:87]
	v_mfma_f32_16x16x32_bf16 v[84:87], v[176:179], v[204:207], v[84:87]
	v_mfma_f32_16x16x32_bf16 v[52:55], v[172:175], v[208:211], v[52:55]
	v_mfma_f32_16x16x32_bf16 v[52:55], v[176:179], v[212:215], v[52:55]
	s_barrier
	s_setprio 0
	ds_read_b128 v[180:183], v141 offset:49152
	ds_read_b128 v[184:187], v141 offset:50176
	ds_read_b128 v[188:191], v141 offset:51200
	ds_read_b128 v[196:199], v141 offset:52224
	ds_read_b128 v[200:203], v141 offset:53248
	ds_read_b128 v[204:207], v141 offset:54272
	ds_read_b128 v[208:211], v141 offset:55296
	ds_read_b128 v[212:215], v141 offset:56320
	s_add_i32 m0, s16, 0x18000
	s_nop 0
	global_load_lds_dwordx4 v1, s[88:89]
	s_nop 0
	s_add_i32 m0, s16, 0x1a000
	s_nop 0
	global_load_lds_dwordx4 v134, s[88:89]
	s_add_u32 s52, s84, 0x40080
	s_addc_u32 s53, s85, 0
	s_add_i32 m0, s16, 0x1c000
	s_nop 0
	global_load_lds_dwordx4 v1, s[52:53]
	s_nop 0
	s_add_i32 m0, s16, 0x1e000
	s_nop 0
	global_load_lds_dwordx4 v134, s[52:53]
	s_nop 0
	s_add_i32 m0, s16, 0x8000
	s_nop 0
	global_load_lds_dwordx4 v136, s[86:87]
	s_nop 0
	s_add_i32 m0, s16, 0xa000
	s_nop 0
	global_load_lds_dwordx4 v137, s[86:87]
	s_waitcnt vmcnt(8)
	s_waitcnt lgkmcnt(0)
	s_setprio 1
	s_barrier
	v_mfma_f32_16x16x32_bf16 v[80:83], v[146:149], v[180:183], v[80:83]
	v_mfma_f32_16x16x32_bf16 v[80:83], v[150:153], v[184:187], v[80:83]
	v_mfma_f32_16x16x32_bf16 v[48:51], v[146:149], v[188:191], v[48:51]
	v_mfma_f32_16x16x32_bf16 v[48:51], v[150:153], v[196:199], v[48:51]
	v_mfma_f32_16x16x32_bf16 v[32:35], v[146:149], v[200:203], v[32:35]
	v_mfma_f32_16x16x32_bf16 v[32:35], v[150:153], v[204:207], v[32:35]
	v_mfma_f32_16x16x32_bf16 v[16:19], v[146:149], v[208:211], v[16:19]
	v_mfma_f32_16x16x32_bf16 v[16:19], v[150:153], v[212:215], v[16:19]
	v_mfma_f32_16x16x32_bf16 v[72:75], v[154:157], v[180:183], v[72:75]
	v_mfma_f32_16x16x32_bf16 v[72:75], v[158:161], v[184:187], v[72:75]
	v_mfma_f32_16x16x32_bf16 v[40:43], v[154:157], v[188:191], v[40:43]
	v_mfma_f32_16x16x32_bf16 v[40:43], v[158:161], v[196:199], v[40:43]
	v_mfma_f32_16x16x32_bf16 v[24:27], v[154:157], v[200:203], v[24:27]
	v_mfma_f32_16x16x32_bf16 v[24:27], v[158:161], v[204:207], v[24:27]
	v_mfma_f32_16x16x32_bf16 v[8:11], v[154:157], v[208:211], v[8:11]
	v_mfma_f32_16x16x32_bf16 v[8:11], v[158:161], v[212:215], v[8:11]
	v_mfma_f32_16x16x32_bf16 v[76:79], v[162:165], v[180:183], v[76:79]
	v_mfma_f32_16x16x32_bf16 v[76:79], v[166:169], v[184:187], v[76:79]
	v_mfma_f32_16x16x32_bf16 v[44:47], v[162:165], v[188:191], v[44:47]
	v_mfma_f32_16x16x32_bf16 v[44:47], v[166:169], v[196:199], v[44:47]
	v_mfma_f32_16x16x32_bf16 v[28:31], v[162:165], v[200:203], v[28:31]
	v_mfma_f32_16x16x32_bf16 v[28:31], v[166:169], v[204:207], v[28:31]
	v_mfma_f32_16x16x32_bf16 v[12:15], v[162:165], v[208:211], v[12:15]
	v_mfma_f32_16x16x32_bf16 v[12:15], v[166:169], v[212:215], v[12:15]
	v_mfma_f32_16x16x32_bf16 v[68:71], v[172:175], v[180:183], v[68:71]
	v_mfma_f32_16x16x32_bf16 v[68:71], v[176:179], v[184:187], v[68:71]
	v_mfma_f32_16x16x32_bf16 v[36:39], v[172:175], v[188:191], v[36:39]
	v_mfma_f32_16x16x32_bf16 v[36:39], v[176:179], v[196:199], v[36:39]
	v_mfma_f32_16x16x32_bf16 v[20:23], v[172:175], v[200:203], v[20:23]
	v_mfma_f32_16x16x32_bf16 v[20:23], v[176:179], v[204:207], v[20:23]
	v_mfma_f32_16x16x32_bf16 v[4:7], v[172:175], v[208:211], v[4:7]
	v_mfma_f32_16x16x32_bf16 v[4:7], v[176:179], v[212:215], v[4:7]
	s_barrier
	s_setprio 0
	s_add_i32 s52, s41, 2
	s_cmp_gt_u32 s41, 13
	s_cbranch_scc1 .LBB0_404
	s_mov_b32 s41, s52
	s_branch .LBB0_383

.LBB0_730:
	s_or_b32 s20, s90, 1
	s_add_i32 s90, s90, 2
	s_mov_b32 s91, s21
	ds_read_b128 v[142:145], v137
	ds_read_b128 v[146:149], v137 offset:1024
	ds_read_b128 v[150:153], v137 offset:2048
	ds_read_b128 v[154:157], v137 offset:3072
	ds_read_b128 v[158:161], v138
	ds_read_b128 v[162:165], v138 offset:1024
	ds_read_b128 v[166:169], v138 offset:2048
	ds_read_b128 v[172:175], v138 offset:3072
	s_lshl_b64 s[96:97], s[20:21], 7
	s_lshl_b64 s[2:3], s[90:91], 7
	s_add_u32 s20, s78, s2
	s_addc_u32 s73, s79, s3
	s_and_b64 s[12:13], s[92:93], exec
	s_cselect_b32 s95, s73, s87
	s_cselect_b32 s94, s20, s86
	s_add_u32 s12, s76, s2
	s_addc_u32 s13, s77, s3
	s_and_b64 s[2:3], s[92:93], exec
	s_cselect_b32 s93, s13, s89
	s_cselect_b32 s92, s12, s88
	s_add_u32 s2, s94, 0x80
	s_addc_u32 s3, s95, 0
	s_add_u32 s12, s92, 0x80
	s_addc_u32 s13, s93, 0
	ds_read_b128 v[176:179], v136
	ds_read_b128 v[180:183], v136 offset:1024
	ds_read_b128 v[184:187], v136 offset:2048
	ds_read_b128 v[188:191], v136 offset:3072
	ds_read_b128 v[196:199], v136 offset:4096
	ds_read_b128 v[200:203], v136 offset:5120
	ds_read_b128 v[204:207], v136 offset:6144
	ds_read_b128 v[208:211], v136 offset:7168
	s_add_u32 s96, s59, s96
	s_addc_u32 s97, s38, s97
	s_add_i32 m0, s43, 0xc000
	s_nop 0
	global_load_lds_dwordx4 v134, s[96:97]
	s_nop 0
	s_add_i32 m0, s43, 0xe000
	s_nop 0
	global_load_lds_dwordx4 v135, s[96:97]
	s_waitcnt vmcnt(8)
	s_waitcnt lgkmcnt(0)
	s_setprio 1
	s_barrier
	v_mfma_f32_16x16x32_bf16 v[70:73], v[142:145], v[176:179], v[70:73]
	v_mfma_f32_16x16x32_bf16 v[70:73], v[146:149], v[180:183], v[70:73]
	v_mfma_f32_16x16x32_bf16 v[74:77], v[142:145], v[184:187], v[74:77]
	v_mfma_f32_16x16x32_bf16 v[74:77], v[146:149], v[188:191], v[74:77]
	v_mfma_f32_16x16x32_bf16 v[78:81], v[142:145], v[196:199], v[78:81]
	v_mfma_f32_16x16x32_bf16 v[78:81], v[146:149], v[200:203], v[78:81]
	v_mfma_f32_16x16x32_bf16 v[82:85], v[142:145], v[204:207], v[82:85]
	v_mfma_f32_16x16x32_bf16 v[82:85], v[146:149], v[208:211], v[82:85]
	v_mfma_f32_16x16x32_bf16 v[86:89], v[150:153], v[176:179], v[86:89]
	v_mfma_f32_16x16x32_bf16 v[86:89], v[154:157], v[180:183], v[86:89]
	v_mfma_f32_16x16x32_bf16 v[90:93], v[150:153], v[184:187], v[90:93]
	v_mfma_f32_16x16x32_bf16 v[90:93], v[154:157], v[188:191], v[90:93]
	v_mfma_f32_16x16x32_bf16 v[94:97], v[150:153], v[196:199], v[94:97]
	v_mfma_f32_16x16x32_bf16 v[94:97], v[154:157], v[200:203], v[94:97]
	v_mfma_f32_16x16x32_bf16 v[98:101], v[150:153], v[204:207], v[98:101]
	v_mfma_f32_16x16x32_bf16 v[98:101], v[154:157], v[208:211], v[98:101]
	v_mfma_f32_16x16x32_bf16 v[102:105], v[158:161], v[176:179], v[102:105]
	v_mfma_f32_16x16x32_bf16 v[102:105], v[162:165], v[180:183], v[102:105]
	v_mfma_f32_16x16x32_bf16 v[106:109], v[158:161], v[184:187], v[106:109]
	v_mfma_f32_16x16x32_bf16 v[106:109], v[162:165], v[188:191], v[106:109]
	v_mfma_f32_16x16x32_bf16 v[110:113], v[158:161], v[196:199], v[110:113]
	v_mfma_f32_16x16x32_bf16 v[110:113], v[162:165], v[200:203], v[110:113]
	v_mfma_f32_16x16x32_bf16 v[114:117], v[158:161], v[204:207], v[114:117]
	v_mfma_f32_16x16x32_bf16 v[114:117], v[162:165], v[208:211], v[114:117]
	v_mfma_f32_16x16x32_bf16 v[118:121], v[166:169], v[176:179], v[118:121]
	v_mfma_f32_16x16x32_bf16 v[118:121], v[172:175], v[180:183], v[118:121]
	v_mfma_f32_16x16x32_bf16 v[122:125], v[166:169], v[184:187], v[122:125]
	v_mfma_f32_16x16x32_bf16 v[122:125], v[172:175], v[188:191], v[122:125]
	v_mfma_f32_16x16x32_bf16 v[126:129], v[166:169], v[196:199], v[126:129]
	v_mfma_f32_16x16x32_bf16 v[126:129], v[172:175], v[200:203], v[126:129]
	v_mfma_f32_16x16x32_bf16 v[130:133], v[166:169], v[204:207], v[130:133]
	v_mfma_f32_16x16x32_bf16 v[130:133], v[172:175], v[208:211], v[130:133]
	s_barrier
	s_setprio 0
	ds_read_b128 v[176:179], v136 offset:16384
	ds_read_b128 v[180:183], v136 offset:17408
	ds_read_b128 v[184:187], v136 offset:18432
	ds_read_b128 v[188:191], v136 offset:19456
	ds_read_b128 v[196:199], v136 offset:20480
	ds_read_b128 v[200:203], v136 offset:21504
	ds_read_b128 v[204:207], v136 offset:22528
	ds_read_b128 v[208:211], v136 offset:23552
	s_add_i32 m0, s43, 0x10000
	s_nop 0
	global_load_lds_dwordx4 v134, s[92:93]
	s_nop 0
	s_add_i32 m0, s43, 0x12000
	s_nop 0
	global_load_lds_dwordx4 v135, s[92:93]
	s_add_u32 s92, s92, s16
	s_addc_u32 s93, s93, 0
	s_add_i32 m0, s43, 0x14000
	s_nop 0
	global_load_lds_dwordx4 v134, s[92:93]
	s_nop 0
	s_add_i32 m0, s43, 0x16000
	s_nop 0
	global_load_lds_dwordx4 v135, s[92:93]
	s_nop 0
	s_add_i32 m0, s43, 0
	s_nop 0
	global_load_lds_dwordx4 v134, s[94:95]
	s_nop 0
	s_add_i32 m0, s43, 0x2000
	s_nop 0
	global_load_lds_dwordx4 v135, s[94:95]
	s_waitcnt vmcnt(8)
	s_waitcnt lgkmcnt(0)
	s_setprio 1
	s_barrier
	v_mfma_f32_16x16x32_bf16 v[4:7], v[142:145], v[176:179], v[6:9]
	v_mfma_f32_16x16x32_bf16 v[22:25], v[150:153], v[176:179], v[22:25]
	v_mfma_f32_16x16x32_bf16 v[8:11], v[142:145], v[184:187], v[10:13]
	v_mfma_f32_16x16x32_bf16 v[26:29], v[150:153], v[184:187], v[26:29]
	v_mfma_f32_16x16x32_bf16 v[14:17], v[142:145], v[196:199], v[14:17]
	v_mfma_f32_16x16x32_bf16 v[30:33], v[150:153], v[196:199], v[30:33]
	v_mfma_f32_16x16x32_bf16 v[18:21], v[142:145], v[204:207], v[18:21]
	v_mfma_f32_16x16x32_bf16 v[34:37], v[150:153], v[204:207], v[34:37]
	v_mfma_f32_16x16x32_bf16 v[4:7], v[146:149], v[180:183], v[4:7]
	v_mfma_f32_16x16x32_bf16 v[22:25], v[154:157], v[180:183], v[22:25]
	v_mfma_f32_16x16x32_bf16 v[10:13], v[146:149], v[188:191], v[8:11]
	v_mfma_f32_16x16x32_bf16 v[26:29], v[154:157], v[188:191], v[26:29]
	v_mfma_f32_16x16x32_bf16 v[14:17], v[146:149], v[200:203], v[14:17]
	v_mfma_f32_16x16x32_bf16 v[30:33], v[154:157], v[200:203], v[30:33]
	v_mfma_f32_16x16x32_bf16 v[18:21], v[146:149], v[208:211], v[18:21]
	v_mfma_f32_16x16x32_bf16 v[34:37], v[154:157], v[208:211], v[34:37]
	v_mfma_f32_16x16x32_bf16 v[38:41], v[158:161], v[176:179], v[38:41]
	v_mfma_f32_16x16x32_bf16 v[54:57], v[166:169], v[176:179], v[54:57]
	v_mfma_f32_16x16x32_bf16 v[42:45], v[158:161], v[184:187], v[42:45]
	v_mfma_f32_16x16x32_bf16 v[58:61], v[166:169], v[184:187], v[58:61]
	v_mfma_f32_16x16x32_bf16 v[46:49], v[158:161], v[196:199], v[46:49]
	v_mfma_f32_16x16x32_bf16 v[62:65], v[166:169], v[196:199], v[62:65]
	v_mfma_f32_16x16x32_bf16 v[50:53], v[158:161], v[204:207], v[50:53]
	v_mfma_f32_16x16x32_bf16 v[66:69], v[166:169], v[204:207], v[66:69]
	v_mfma_f32_16x16x32_bf16 v[38:41], v[162:165], v[180:183], v[38:41]
	v_mfma_f32_16x16x32_bf16 v[54:57], v[172:175], v[180:183], v[54:57]
	v_mfma_f32_16x16x32_bf16 v[42:45], v[162:165], v[188:191], v[42:45]
	v_mfma_f32_16x16x32_bf16 v[58:61], v[172:175], v[188:191], v[58:61]
	v_mfma_f32_16x16x32_bf16 v[46:49], v[162:165], v[200:203], v[46:49]
	v_mfma_f32_16x16x32_bf16 v[62:65], v[172:175], v[200:203], v[62:65]
	v_mfma_f32_16x16x32_bf16 v[50:53], v[162:165], v[208:211], v[50:53]
	v_mfma_f32_16x16x32_bf16 v[66:69], v[172:175], v[208:211], v[66:69]
	s_barrier
	s_setprio 0
	ds_read_b128 v[142:145], v139
	ds_read_b128 v[146:149], v139 offset:1024
	ds_read_b128 v[150:153], v139 offset:2048
	ds_read_b128 v[154:157], v139 offset:3072
	ds_read_b128 v[158:161], v140
	ds_read_b128 v[162:165], v140 offset:1024
	ds_read_b128 v[166:169], v140 offset:2048
	ds_read_b128 v[172:175], v140 offset:3072
	ds_read_b128 v[176:179], v136 offset:32768
	ds_read_b128 v[180:183], v136 offset:33792
	ds_read_b128 v[184:187], v136 offset:34816
	ds_read_b128 v[188:191], v136 offset:35840
	ds_read_b128 v[196:199], v136 offset:36864
	ds_read_b128 v[200:203], v136 offset:37888
	ds_read_b128 v[204:207], v136 offset:38912
	ds_read_b128 v[208:211], v136 offset:39936
	s_add_u32 s92, s94, s16
	s_addc_u32 s93, s95, 0
	s_add_i32 m0, s43, 0x4000
	s_nop 0
	global_load_lds_dwordx4 v134, s[92:93]
	s_nop 0
	s_add_i32 m0, s43, 0x6000
	s_nop 0
	global_load_lds_dwordx4 v135, s[92:93]
	s_waitcnt vmcnt(8)
	s_waitcnt lgkmcnt(0)
	s_setprio 1
	s_barrier
	v_mfma_f32_16x16x32_bf16 v[70:73], v[142:145], v[176:179], v[70:73]
	v_mfma_f32_16x16x32_bf16 v[70:73], v[146:149], v[180:183], v[70:73]
	v_mfma_f32_16x16x32_bf16 v[74:77], v[142:145], v[184:187], v[74:77]
	v_mfma_f32_16x16x32_bf16 v[74:77], v[146:149], v[188:191], v[74:77]
	v_mfma_f32_16x16x32_bf16 v[78:81], v[142:145], v[196:199], v[78:81]
	v_mfma_f32_16x16x32_bf16 v[78:81], v[146:149], v[200:203], v[78:81]
	v_mfma_f32_16x16x32_bf16 v[82:85], v[142:145], v[204:207], v[82:85]
	v_mfma_f32_16x16x32_bf16 v[82:85], v[146:149], v[208:211], v[82:85]
	v_mfma_f32_16x16x32_bf16 v[86:89], v[150:153], v[176:179], v[86:89]
	v_mfma_f32_16x16x32_bf16 v[86:89], v[154:157], v[180:183], v[86:89]
	v_mfma_f32_16x16x32_bf16 v[90:93], v[150:153], v[184:187], v[90:93]
	v_mfma_f32_16x16x32_bf16 v[90:93], v[154:157], v[188:191], v[90:93]
	v_mfma_f32_16x16x32_bf16 v[94:97], v[150:153], v[196:199], v[94:97]
	v_mfma_f32_16x16x32_bf16 v[94:97], v[154:157], v[200:203], v[94:97]
	v_mfma_f32_16x16x32_bf16 v[98:101], v[150:153], v[204:207], v[98:101]
	v_mfma_f32_16x16x32_bf16 v[98:101], v[154:157], v[208:211], v[98:101]
	v_mfma_f32_16x16x32_bf16 v[102:105], v[158:161], v[176:179], v[102:105]
	v_mfma_f32_16x16x32_bf16 v[102:105], v[162:165], v[180:183], v[102:105]
	v_mfma_f32_16x16x32_bf16 v[106:109], v[158:161], v[184:187], v[106:109]
	v_mfma_f32_16x16x32_bf16 v[106:109], v[162:165], v[188:191], v[106:109]
	v_mfma_f32_16x16x32_bf16 v[110:113], v[158:161], v[196:199], v[110:113]
	v_mfma_f32_16x16x32_bf16 v[110:113], v[162:165], v[200:203], v[110:113]
	v_mfma_f32_16x16x32_bf16 v[114:117], v[158:161], v[204:207], v[114:117]
	v_mfma_f32_16x16x32_bf16 v[114:117], v[162:165], v[208:211], v[114:117]
	v_mfma_f32_16x16x32_bf16 v[118:121], v[166:169], v[176:179], v[118:121]
	v_mfma_f32_16x16x32_bf16 v[118:121], v[172:175], v[180:183], v[118:121]
	v_mfma_f32_16x16x32_bf16 v[122:125], v[166:169], v[184:187], v[122:125]
	v_mfma_f32_16x16x32_bf16 v[122:125], v[172:175], v[188:191], v[122:125]
	v_mfma_f32_16x16x32_bf16 v[126:129], v[166:169], v[196:199], v[126:129]
	v_mfma_f32_16x16x32_bf16 v[126:129], v[172:175], v[200:203], v[126:129]
	v_mfma_f32_16x16x32_bf16 v[130:133], v[166:169], v[204:207], v[130:133]
	v_mfma_f32_16x16x32_bf16 v[130:133], v[172:175], v[208:211], v[130:133]
	s_barrier
	s_setprio 0
	ds_read_b128 v[176:179], v136 offset:49152
	ds_read_b128 v[180:183], v136 offset:50176
	ds_read_b128 v[184:187], v136 offset:51200
	ds_read_b128 v[188:191], v136 offset:52224
	ds_read_b128 v[196:199], v136 offset:53248
	ds_read_b128 v[200:203], v136 offset:54272
	ds_read_b128 v[204:207], v136 offset:55296
	ds_read_b128 v[208:211], v136 offset:56320
	s_add_i32 m0, s43, 0x18000
	s_nop 0
	global_load_lds_dwordx4 v134, s[12:13]
	s_nop 0
	s_add_i32 m0, s43, 0x1a000
	s_nop 0
	global_load_lds_dwordx4 v135, s[12:13]
	s_add_u32 s12, s12, s16
	s_addc_u32 s13, s13, 0
	s_add_i32 m0, s43, 0x1c000
	s_nop 0
	global_load_lds_dwordx4 v134, s[12:13]
	s_nop 0
	s_add_i32 m0, s43, 0x1e000
	s_nop 0
	global_load_lds_dwordx4 v135, s[12:13]
	s_nop 0
	s_add_i32 m0, s43, 0x8000
	s_nop 0
	global_load_lds_dwordx4 v134, s[2:3]
	s_nop 0
	s_add_i32 m0, s43, 0xa000
	s_nop 0
	global_load_lds_dwordx4 v135, s[2:3]
	s_waitcnt vmcnt(8)
	s_waitcnt lgkmcnt(0)
	s_setprio 1
	s_barrier
	v_mfma_f32_16x16x32_bf16 v[4:7], v[142:145], v[176:179], v[4:7]
	v_mfma_f32_16x16x32_bf16 v[22:25], v[150:153], v[176:179], v[22:25]
	v_mfma_f32_16x16x32_bf16 v[10:13], v[142:145], v[184:187], v[10:13]
	v_mfma_f32_16x16x32_bf16 v[26:29], v[150:153], v[184:187], v[26:29]
	v_mfma_f32_16x16x32_bf16 v[14:17], v[142:145], v[196:199], v[14:17]
	v_mfma_f32_16x16x32_bf16 v[30:33], v[150:153], v[196:199], v[30:33]
	v_mfma_f32_16x16x32_bf16 v[18:21], v[142:145], v[204:207], v[18:21]
	v_mfma_f32_16x16x32_bf16 v[34:37], v[150:153], v[204:207], v[34:37]
	v_mfma_f32_16x16x32_bf16 v[6:9], v[146:149], v[180:183], v[4:7]
	v_mfma_f32_16x16x32_bf16 v[22:25], v[154:157], v[180:183], v[22:25]
	v_mfma_f32_16x16x32_bf16 v[10:13], v[146:149], v[188:191], v[10:13]
	v_mfma_f32_16x16x32_bf16 v[26:29], v[154:157], v[188:191], v[26:29]
	v_mfma_f32_16x16x32_bf16 v[14:17], v[146:149], v[200:203], v[14:17]
	v_mfma_f32_16x16x32_bf16 v[30:33], v[154:157], v[200:203], v[30:33]
	v_mfma_f32_16x16x32_bf16 v[18:21], v[146:149], v[208:211], v[18:21]
	v_mfma_f32_16x16x32_bf16 v[34:37], v[154:157], v[208:211], v[34:37]
	v_mfma_f32_16x16x32_bf16 v[38:41], v[158:161], v[176:179], v[38:41]
	v_mfma_f32_16x16x32_bf16 v[54:57], v[166:169], v[176:179], v[54:57]
	v_mfma_f32_16x16x32_bf16 v[42:45], v[158:161], v[184:187], v[42:45]
	v_mfma_f32_16x16x32_bf16 v[58:61], v[166:169], v[184:187], v[58:61]
	v_mfma_f32_16x16x32_bf16 v[46:49], v[158:161], v[196:199], v[46:49]
	v_mfma_f32_16x16x32_bf16 v[62:65], v[166:169], v[196:199], v[62:65]
	v_mfma_f32_16x16x32_bf16 v[50:53], v[158:161], v[204:207], v[50:53]
	v_mfma_f32_16x16x32_bf16 v[66:69], v[166:169], v[204:207], v[66:69]
	v_mfma_f32_16x16x32_bf16 v[38:41], v[162:165], v[180:183], v[38:41]
	v_mfma_f32_16x16x32_bf16 v[54:57], v[172:175], v[180:183], v[54:57]
	v_mfma_f32_16x16x32_bf16 v[42:45], v[162:165], v[188:191], v[42:45]
	v_mfma_f32_16x16x32_bf16 v[58:61], v[172:175], v[188:191], v[58:61]
	v_mfma_f32_16x16x32_bf16 v[46:49], v[162:165], v[200:203], v[46:49]
	v_mfma_f32_16x16x32_bf16 v[62:65], v[172:175], v[200:203], v[62:65]
	v_mfma_f32_16x16x32_bf16 v[50:53], v[162:165], v[208:211], v[50:53]
	v_mfma_f32_16x16x32_bf16 v[66:69], v[172:175], v[208:211], v[66:69]
	s_barrier
	s_setprio 0
	s_cmp_ge_u32 s90, s55
	s_cbranch_scc1 .LBB0_848

.LBB0_1192:
	s_lshl_b32 s12, s29, 7
	s_add_u32 s90, s62, s12
	s_addc_u32 s91, s63, 0
	s_add_u32 s13, s90, 0x100
	ds_read_b128 v[138:141], v134
	ds_read_b128 v[142:145], v134 offset:1024
	ds_read_b128 v[154:157], v134 offset:2048
	ds_read_b128 v[158:161], v134 offset:3072
	ds_read_b128 v[162:165], v135
	ds_read_b128 v[166:169], v135 offset:1024
	ds_read_b128 v[172:175], v135 offset:2048
	ds_read_b128 v[176:179], v135 offset:3072
	s_addc_u32 s88, s91, 0
	s_and_b64 s[2:3], s[86:87], exec
	s_cselect_b32 s89, s33, s88
	s_cselect_b32 s88, s39, s13
	s_add_u32 s2, s64, s12
	s_addc_u32 s3, s65, 0
	s_add_u32 s12, s2, 0x100
	s_addc_u32 s13, s3, 0
	s_and_b64 s[2:3], s[86:87], exec
	s_cselect_b32 s3, s54, s13
	s_cselect_b32 s2, s47, s12
	s_add_u32 s12, s88, 0x80
	s_addc_u32 s13, s89, 0
	s_add_u32 s86, s2, 0x80
	s_addc_u32 s87, s3, 0
	ds_read_b128 v[180:183], v152
	ds_read_b128 v[184:187], v152 offset:1024
	ds_read_b128 v[196:199], v152 offset:2048
	ds_read_b128 v[200:203], v152 offset:3072
	ds_read_b128 v[204:207], v152 offset:4096
	ds_read_b128 v[208:211], v152 offset:5120
	ds_read_b128 v[212:215], v152 offset:6144
	ds_read_b128 v[216:219], v152 offset:7168
	s_add_u32 s90, s90, 0x40080
	s_addc_u32 s91, s91, 0
	s_add_i32 m0, s69, 0xc000
	s_nop 0
	global_load_lds_dwordx4 v147, s[90:91]
	s_nop 0
	s_add_i32 m0, s69, 0xe000
	s_nop 0
	global_load_lds_dwordx4 v148, s[90:91]
	s_waitcnt vmcnt(8)
	s_waitcnt lgkmcnt(0)
	s_setprio 1
	s_barrier
	v_mfma_f32_16x16x32_bf16 v[124:127], v[138:141], v[180:183], v[124:127]
	v_mfma_f32_16x16x32_bf16 v[124:127], v[142:145], v[184:187], v[124:127]
	v_mfma_f32_16x16x32_bf16 v[108:111], v[138:141], v[196:199], v[108:111]
	v_mfma_f32_16x16x32_bf16 v[108:111], v[142:145], v[200:203], v[108:111]
	v_mfma_f32_16x16x32_bf16 v[92:95], v[138:141], v[204:207], v[92:95]
	v_mfma_f32_16x16x32_bf16 v[92:95], v[142:145], v[208:211], v[92:95]
	v_mfma_f32_16x16x32_bf16 v[76:79], v[138:141], v[212:215], v[76:79]
	v_mfma_f32_16x16x32_bf16 v[76:79], v[142:145], v[216:219], v[76:79]
	v_mfma_f32_16x16x32_bf16 v[116:119], v[154:157], v[180:183], v[116:119]
	v_mfma_f32_16x16x32_bf16 v[116:119], v[158:161], v[184:187], v[116:119]
	v_mfma_f32_16x16x32_bf16 v[100:103], v[154:157], v[196:199], v[100:103]
	v_mfma_f32_16x16x32_bf16 v[100:103], v[158:161], v[200:203], v[100:103]
	v_mfma_f32_16x16x32_bf16 v[84:87], v[154:157], v[204:207], v[84:87]
	v_mfma_f32_16x16x32_bf16 v[84:87], v[158:161], v[208:211], v[84:87]
	v_mfma_f32_16x16x32_bf16 v[64:67], v[154:157], v[212:215], v[64:67]
	v_mfma_f32_16x16x32_bf16 v[64:67], v[158:161], v[216:219], v[64:67]
	v_mfma_f32_16x16x32_bf16 v[128:131], v[162:165], v[180:183], v[128:131]
	v_mfma_f32_16x16x32_bf16 v[128:131], v[166:169], v[184:187], v[128:131]
	v_mfma_f32_16x16x32_bf16 v[112:115], v[162:165], v[196:199], v[112:115]
	v_mfma_f32_16x16x32_bf16 v[112:115], v[166:169], v[200:203], v[112:115]
	v_mfma_f32_16x16x32_bf16 v[96:99], v[162:165], v[204:207], v[96:99]
	v_mfma_f32_16x16x32_bf16 v[96:99], v[166:169], v[208:211], v[96:99]
	v_mfma_f32_16x16x32_bf16 v[80:83], v[162:165], v[212:215], v[80:83]
	v_mfma_f32_16x16x32_bf16 v[80:83], v[166:169], v[216:219], v[80:83]
	v_mfma_f32_16x16x32_bf16 v[120:123], v[172:175], v[180:183], v[120:123]
	v_mfma_f32_16x16x32_bf16 v[120:123], v[176:179], v[184:187], v[120:123]
	v_mfma_f32_16x16x32_bf16 v[104:107], v[172:175], v[196:199], v[104:107]
	v_mfma_f32_16x16x32_bf16 v[104:107], v[176:179], v[200:203], v[104:107]
	v_mfma_f32_16x16x32_bf16 v[88:91], v[172:175], v[204:207], v[88:91]
	v_mfma_f32_16x16x32_bf16 v[88:91], v[176:179], v[208:211], v[88:91]
	v_mfma_f32_16x16x32_bf16 v[72:75], v[172:175], v[212:215], v[72:75]
	v_mfma_f32_16x16x32_bf16 v[72:75], v[176:179], v[216:219], v[72:75]
	s_barrier
	s_setprio 0
	ds_read_b128 v[180:183], v152 offset:16384
	ds_read_b128 v[184:187], v152 offset:17408
	ds_read_b128 v[196:199], v152 offset:18432
	ds_read_b128 v[200:203], v152 offset:19456
	ds_read_b128 v[204:207], v152 offset:20480
	ds_read_b128 v[208:211], v152 offset:21504
	ds_read_b128 v[212:215], v152 offset:22528
	ds_read_b128 v[216:219], v152 offset:23552
	s_add_i32 m0, s69, 0x10000
	s_nop 0
	global_load_lds_dwordx4 v1, s[2:3]
	s_nop 0
	s_add_i32 m0, s69, 0x12000
	s_nop 0
	global_load_lds_dwordx4 v146, s[2:3]
	s_add_u32 s90, s2, 0x40000
	s_addc_u32 s91, s3, 0
	s_add_i32 m0, s69, 0x14000
	s_nop 0
	global_load_lds_dwordx4 v1, s[90:91]
	s_nop 0
	s_add_i32 m0, s69, 0x16000
	s_nop 0
	global_load_lds_dwordx4 v146, s[90:91]
	s_nop 0
	s_add_i32 m0, s69, 0
	s_nop 0
	global_load_lds_dwordx4 v147, s[88:89]
	s_nop 0
	s_add_i32 m0, s69, 0x2000
	s_nop 0
	global_load_lds_dwordx4 v148, s[88:89]
	s_waitcnt vmcnt(8)
	s_waitcnt lgkmcnt(0)
	s_setprio 1
	s_barrier
	v_mfma_f32_16x16x32_bf16 v[60:63], v[138:141], v[180:183], v[60:63]
	v_mfma_f32_16x16x32_bf16 v[60:63], v[142:145], v[184:187], v[60:63]
	v_mfma_f32_16x16x32_bf16 v[44:47], v[138:141], v[196:199], v[44:47]
	v_mfma_f32_16x16x32_bf16 v[44:47], v[142:145], v[200:203], v[44:47]
	v_mfma_f32_16x16x32_bf16 v[28:31], v[138:141], v[204:207], v[28:31]
	v_mfma_f32_16x16x32_bf16 v[28:31], v[142:145], v[208:211], v[28:31]
	v_mfma_f32_16x16x32_bf16 v[12:15], v[138:141], v[212:215], v[12:15]
	v_mfma_f32_16x16x32_bf16 v[12:15], v[142:145], v[216:219], v[12:15]
	v_mfma_f32_16x16x32_bf16 v[52:55], v[154:157], v[180:183], v[52:55]
	v_mfma_f32_16x16x32_bf16 v[52:55], v[158:161], v[184:187], v[52:55]
	v_mfma_f32_16x16x32_bf16 v[36:39], v[154:157], v[196:199], v[36:39]
	v_mfma_f32_16x16x32_bf16 v[36:39], v[158:161], v[200:203], v[36:39]
	v_mfma_f32_16x16x32_bf16 v[20:23], v[154:157], v[204:207], v[20:23]
	v_mfma_f32_16x16x32_bf16 v[20:23], v[158:161], v[208:211], v[20:23]
	v_mfma_f32_16x16x32_bf16 v[4:7], v[154:157], v[212:215], v[4:7]
	v_mfma_f32_16x16x32_bf16 v[4:7], v[158:161], v[216:219], v[4:7]
	v_mfma_f32_16x16x32_bf16 v[68:71], v[162:165], v[180:183], v[68:71]
	v_mfma_f32_16x16x32_bf16 v[68:71], v[166:169], v[184:187], v[68:71]
	v_mfma_f32_16x16x32_bf16 v[48:51], v[162:165], v[196:199], v[48:51]
	v_mfma_f32_16x16x32_bf16 v[48:51], v[166:169], v[200:203], v[48:51]
	v_mfma_f32_16x16x32_bf16 v[32:35], v[162:165], v[204:207], v[32:35]
	v_mfma_f32_16x16x32_bf16 v[32:35], v[166:169], v[208:211], v[32:35]
	v_mfma_f32_16x16x32_bf16 v[16:19], v[162:165], v[212:215], v[16:19]
	v_mfma_f32_16x16x32_bf16 v[16:19], v[166:169], v[216:219], v[16:19]
	v_mfma_f32_16x16x32_bf16 v[56:59], v[172:175], v[180:183], v[56:59]
	v_mfma_f32_16x16x32_bf16 v[56:59], v[176:179], v[184:187], v[56:59]
	v_mfma_f32_16x16x32_bf16 v[40:43], v[172:175], v[196:199], v[40:43]
	v_mfma_f32_16x16x32_bf16 v[40:43], v[176:179], v[200:203], v[40:43]
	v_mfma_f32_16x16x32_bf16 v[24:27], v[172:175], v[204:207], v[24:27]
	v_mfma_f32_16x16x32_bf16 v[24:27], v[176:179], v[208:211], v[24:27]
	v_mfma_f32_16x16x32_bf16 v[8:11], v[172:175], v[212:215], v[8:11]
	v_mfma_f32_16x16x32_bf16 v[8:11], v[176:179], v[216:219], v[8:11]
	s_barrier
	s_setprio 0
	ds_read_b128 v[138:141], v136
	ds_read_b128 v[142:145], v136 offset:1024
	ds_read_b128 v[154:157], v136 offset:2048
	ds_read_b128 v[158:161], v136 offset:3072
	ds_read_b128 v[162:165], v137
	ds_read_b128 v[166:169], v137 offset:1024
	ds_read_b128 v[172:175], v137 offset:2048
	ds_read_b128 v[176:179], v137 offset:3072
	ds_read_b128 v[180:183], v152 offset:32768
	ds_read_b128 v[184:187], v152 offset:33792
	ds_read_b128 v[196:199], v152 offset:34816
	ds_read_b128 v[200:203], v152 offset:35840
	ds_read_b128 v[204:207], v152 offset:36864
	ds_read_b128 v[208:211], v152 offset:37888
	ds_read_b128 v[212:215], v152 offset:38912
	ds_read_b128 v[216:219], v152 offset:39936
	s_add_u32 s88, s88, 0x40000
	s_addc_u32 s89, s89, 0
	s_add_i32 m0, s69, 0x4000
	s_nop 0
	global_load_lds_dwordx4 v147, s[88:89]
	s_nop 0
	s_add_i32 m0, s69, 0x6000
	s_nop 0
	global_load_lds_dwordx4 v148, s[88:89]
	s_waitcnt vmcnt(8)
	s_waitcnt lgkmcnt(0)
	s_setprio 1
	s_barrier
	v_mfma_f32_16x16x32_bf16 v[124:127], v[138:141], v[180:183], v[124:127]
	v_mfma_f32_16x16x32_bf16 v[124:127], v[142:145], v[184:187], v[124:127]
	v_mfma_f32_16x16x32_bf16 v[108:111], v[138:141], v[196:199], v[108:111]
	v_mfma_f32_16x16x32_bf16 v[108:111], v[142:145], v[200:203], v[108:111]
	v_mfma_f32_16x16x32_bf16 v[92:95], v[138:141], v[204:207], v[92:95]
	v_mfma_f32_16x16x32_bf16 v[92:95], v[142:145], v[208:211], v[92:95]
	v_mfma_f32_16x16x32_bf16 v[76:79], v[138:141], v[212:215], v[76:79]
	v_mfma_f32_16x16x32_bf16 v[76:79], v[142:145], v[216:219], v[76:79]
	v_mfma_f32_16x16x32_bf16 v[116:119], v[154:157], v[180:183], v[116:119]
	v_mfma_f32_16x16x32_bf16 v[116:119], v[158:161], v[184:187], v[116:119]
	v_mfma_f32_16x16x32_bf16 v[100:103], v[154:157], v[196:199], v[100:103]
	v_mfma_f32_16x16x32_bf16 v[100:103], v[158:161], v[200:203], v[100:103]
	v_mfma_f32_16x16x32_bf16 v[84:87], v[154:157], v[204:207], v[84:87]
	v_mfma_f32_16x16x32_bf16 v[84:87], v[158:161], v[208:211], v[84:87]
	v_mfma_f32_16x16x32_bf16 v[64:67], v[154:157], v[212:215], v[64:67]
	v_mfma_f32_16x16x32_bf16 v[64:67], v[158:161], v[216:219], v[64:67]
	v_mfma_f32_16x16x32_bf16 v[128:131], v[162:165], v[180:183], v[128:131]
	v_mfma_f32_16x16x32_bf16 v[128:131], v[166:169], v[184:187], v[128:131]
	v_mfma_f32_16x16x32_bf16 v[112:115], v[162:165], v[196:199], v[112:115]
	v_mfma_f32_16x16x32_bf16 v[112:115], v[166:169], v[200:203], v[112:115]
	v_mfma_f32_16x16x32_bf16 v[96:99], v[162:165], v[204:207], v[96:99]
	v_mfma_f32_16x16x32_bf16 v[96:99], v[166:169], v[208:211], v[96:99]
	v_mfma_f32_16x16x32_bf16 v[80:83], v[162:165], v[212:215], v[80:83]
	v_mfma_f32_16x16x32_bf16 v[80:83], v[166:169], v[216:219], v[80:83]
	v_mfma_f32_16x16x32_bf16 v[120:123], v[172:175], v[180:183], v[120:123]
	v_mfma_f32_16x16x32_bf16 v[120:123], v[176:179], v[184:187], v[120:123]
	v_mfma_f32_16x16x32_bf16 v[104:107], v[172:175], v[196:199], v[104:107]
	v_mfma_f32_16x16x32_bf16 v[104:107], v[176:179], v[200:203], v[104:107]
	v_mfma_f32_16x16x32_bf16 v[88:91], v[172:175], v[204:207], v[88:91]
	v_mfma_f32_16x16x32_bf16 v[88:91], v[176:179], v[208:211], v[88:91]
	v_mfma_f32_16x16x32_bf16 v[72:75], v[172:175], v[212:215], v[72:75]
	v_mfma_f32_16x16x32_bf16 v[72:75], v[176:179], v[216:219], v[72:75]
	s_barrier
	s_setprio 0
	ds_read_b128 v[180:183], v152 offset:49152
	ds_read_b128 v[184:187], v152 offset:50176
	ds_read_b128 v[196:199], v152 offset:51200
	ds_read_b128 v[200:203], v152 offset:52224
	ds_read_b128 v[204:207], v152 offset:53248
	ds_read_b128 v[208:211], v152 offset:54272
	ds_read_b128 v[212:215], v152 offset:55296
	ds_read_b128 v[216:219], v152 offset:56320
	s_add_i32 m0, s69, 0x18000
	s_nop 0
	global_load_lds_dwordx4 v1, s[86:87]
	s_nop 0
	s_add_i32 m0, s69, 0x1a000
	s_nop 0
	global_load_lds_dwordx4 v146, s[86:87]
	s_add_u32 s2, s2, 0x40080
	s_addc_u32 s3, s3, 0
	s_add_i32 m0, s69, 0x1c000
	s_nop 0
	global_load_lds_dwordx4 v1, s[2:3]
	s_nop 0
	s_add_i32 m0, s69, 0x1e000
	s_nop 0
	global_load_lds_dwordx4 v146, s[2:3]
	s_nop 0
	s_add_i32 m0, s69, 0x8000
	s_nop 0
	global_load_lds_dwordx4 v147, s[12:13]
	s_nop 0
	s_add_i32 m0, s69, 0xa000
	s_nop 0
	global_load_lds_dwordx4 v148, s[12:13]
	s_waitcnt vmcnt(8)
	s_waitcnt lgkmcnt(0)
	s_setprio 1
	s_barrier
	v_mfma_f32_16x16x32_bf16 v[60:63], v[138:141], v[180:183], v[60:63]
	v_mfma_f32_16x16x32_bf16 v[60:63], v[142:145], v[184:187], v[60:63]
	v_mfma_f32_16x16x32_bf16 v[44:47], v[138:141], v[196:199], v[44:47]
	v_mfma_f32_16x16x32_bf16 v[44:47], v[142:145], v[200:203], v[44:47]
	v_mfma_f32_16x16x32_bf16 v[28:31], v[138:141], v[204:207], v[28:31]
	v_mfma_f32_16x16x32_bf16 v[28:31], v[142:145], v[208:211], v[28:31]
	v_mfma_f32_16x16x32_bf16 v[12:15], v[138:141], v[212:215], v[12:15]
	v_mfma_f32_16x16x32_bf16 v[12:15], v[142:145], v[216:219], v[12:15]
	v_mfma_f32_16x16x32_bf16 v[52:55], v[154:157], v[180:183], v[52:55]
	v_mfma_f32_16x16x32_bf16 v[52:55], v[158:161], v[184:187], v[52:55]
	v_mfma_f32_16x16x32_bf16 v[36:39], v[154:157], v[196:199], v[36:39]
	v_mfma_f32_16x16x32_bf16 v[36:39], v[158:161], v[200:203], v[36:39]
	v_mfma_f32_16x16x32_bf16 v[20:23], v[154:157], v[204:207], v[20:23]
	v_mfma_f32_16x16x32_bf16 v[20:23], v[158:161], v[208:211], v[20:23]
	v_mfma_f32_16x16x32_bf16 v[4:7], v[154:157], v[212:215], v[4:7]
	v_mfma_f32_16x16x32_bf16 v[4:7], v[158:161], v[216:219], v[4:7]
	v_mfma_f32_16x16x32_bf16 v[68:71], v[162:165], v[180:183], v[68:71]
	v_mfma_f32_16x16x32_bf16 v[68:71], v[166:169], v[184:187], v[68:71]
	v_mfma_f32_16x16x32_bf16 v[48:51], v[162:165], v[196:199], v[48:51]
	v_mfma_f32_16x16x32_bf16 v[48:51], v[166:169], v[200:203], v[48:51]
	v_mfma_f32_16x16x32_bf16 v[32:35], v[162:165], v[204:207], v[32:35]
	v_mfma_f32_16x16x32_bf16 v[32:35], v[166:169], v[208:211], v[32:35]
	v_mfma_f32_16x16x32_bf16 v[16:19], v[162:165], v[212:215], v[16:19]
	v_mfma_f32_16x16x32_bf16 v[16:19], v[166:169], v[216:219], v[16:19]
	v_mfma_f32_16x16x32_bf16 v[56:59], v[172:175], v[180:183], v[56:59]
	v_mfma_f32_16x16x32_bf16 v[56:59], v[176:179], v[184:187], v[56:59]
	v_mfma_f32_16x16x32_bf16 v[40:43], v[172:175], v[196:199], v[40:43]
	v_mfma_f32_16x16x32_bf16 v[40:43], v[176:179], v[200:203], v[40:43]
	v_mfma_f32_16x16x32_bf16 v[24:27], v[172:175], v[204:207], v[24:27]
	v_mfma_f32_16x16x32_bf16 v[24:27], v[176:179], v[208:211], v[24:27]
	v_mfma_f32_16x16x32_bf16 v[8:11], v[172:175], v[212:215], v[8:11]
	v_mfma_f32_16x16x32_bf16 v[8:11], v[176:179], v[216:219], v[8:11]
	s_barrier
	s_setprio 0
	s_add_i32 s2, s29, 2
	s_cmp_gt_u32 s29, 13
	s_cbranch_scc1 .LBB0_1196
	s_mov_b32 s29, s2
	s_branch .LBB0_1072
